# phase-A in-proj k-loop rewritten: LDS-DMA (global_load_lds) 4-unit ring, swizzled 128B rows, rn loads hoisted
# baseline (speedup 1.0000x reference)
; #define GLOAD(dst, kt_) _Pragma("unroll") for (int i = 0; i < NCH; ++i) { dst[i] = (i < NCHW) ? ldw(i, tid >> 3, (kt_) * 64 + (tid & 7) * 8) : ldx(i - NCHW, tid >> 3, (kt_) * 64 + (tid & 7) * 8); }
; #define LSTORE(src, base) _Pragma("unroll") for (int i = 0; i < NCH; ++i) { const int c = tid + 256 * i; *(u32x4*)((base) + (c >> 3) * 144 + (c & 7) * 16) = src[i]; }
; template <int WGN, int INS, int IMS, bool DB, class LdW, class LdX>
; DI void gemm_core(f32x16 (&acc)[INS][IMS], const int KT, LdW ldw, LdX ldx, char* lds, const int tid) {
;   constexpr int WGM = 4 / WGN;
;   constexpr int WROWS = WGN * 32 * INS, XROWS = WGM * 32 * IMS, NROWS = WROWS + XROWS, NCH = NROWS / 32, NCHW = WROWS / 32, BUFB = NROWS * 144;
;   const int lane = tid & 63, wid = tid >> 6, l31 = lane & 31, hi = lane >> 5;
;   const int wn = (WGN == 2) ? (wid >> 1) : wid, wm = (WGN == 2) ? (wid & 1) : 0;
;   const int offa = (wn * 32 * INS + l31) * 144 + hi * 16;
;   const int offb = (WROWS + wm * 32 * IMS + l31) * 144 + hi * 16;
; #pragma unroll
;   for (int a = 0; a < INS; ++a)
; #pragma unroll
;     for (int b = 0; b < IMS; ++b)
; #pragma unroll
;       for (int r = 0; r < 16; ++r) acc[a][b][r] = 0.f;
;     ...
;   if (DB) {
;     u32x4 preA[NCH], preB[NCH];
;     GLOAD(preA, 0)
;     GLOAD(preB, 1)
;     __syncthreads();
;     LSTORE(preA, lds)
;     __syncthreads();
; template <int NTW>
; DI void inproj_tile(const Params& p, int l, int mt, int ntile, char* lds) {
;     ...
;   for (int im = 0; im < 2; ++im) {
;     const int tl = wm * 64 + im * 32 + l31;
;     const float r = rn[(size_t)mt * 128 + tl];
.LBB0_163:
	s_lshl_b32 s0, s26, 4
	s_and_b32 s0, s0, 0x70
	s_bfe_u32 s1, s26, 0x40003
	s_or_b32 s4, s0, s1
	s_mov_b64 s[0:1], 0
	s_add_u32 s27, s90, s0
	s_addc_u32 s28, s91, s1
	s_lshl_b32 s0, s26, 1
	s_and_b32 s0, s0, 0xffffff00
	v_readlane_b32 s2, v234, 24
	s_ashr_i32 s1, s0, 31
	s_mulk_i32 s2, 0xd00
	s_add_u32 s2, s0, s2
	s_addc_u32 s3, s1, 0
	s_lshl_b64 s[2:3], s[2:3], 11
	s_add_u32 s2, s27, s2
	s_addc_u32 s3, s28, s3
	s_lshl_b32 s80, s4, 7
	s_lshl_b32 s4, s4, 18
	s_add_u32 s24, s27, s4
	s_addc_u32 s25, s28, 0
	s_add_u32 s4, s24, 0x2a40000
	s_addc_u32 s5, s25, 0
	v_mov_b32_e32 v181, v176
	v_and_b32_e32 v183, 0x5f, v181
	v_lshrrev_b32_e32 v185, 3, v181
	v_or_b32_e32 v254, s80, v183
	v_lshlrev_b32_e32 v254, 2, v254
	s_add_u32 s14, s27, 0x4a40000
	s_addc_u32 s15, s28, 0
	global_load_dword v252, v254, s[14:15]
	global_load_dword v253, v254, s[14:15] offset:128
	v_and_b32_e32 v220, 63, v181
	v_lshrrev_b32_e32 v221, 6, v181
	v_lshrrev_b32_e32 v222, 3, v220
	v_readfirstlane_b32 s13, v221
	v_and_b32_e32 v223, 7, v220
	v_bfe_u32 v224, v220, 4, 2
	v_xor_b32_e32 v223, v223, v224
	v_lshlrev_b32_e32 v223, 4, v223
	v_and_b32_e32 v224, 1, v221
	v_lshrrev_b32_e32 v225, 1, v221
	v_lshlrev_b32_e32 v224, 5, v224
	v_lshl_add_u32 v224, v225, 7, v224
	v_add_u32_e32 v224, v224, v222
	v_lshl_add_u32 v225, v221, 5, v222
	v_lshl_or_b32 v210, v224, 11, v223
	v_lshl_or_b32 v216, v225, 11, v223
	v_xor_b32_e32 v224, 64, v210
	v_xor_b32_e32 v225, 64, v216
	v_add_u32_e32 v211, 0x3c00, v224
	v_add_u32_e32 v217, 0x3c00, v225
	v_add_u32_e32 v212, 0x7800, v210
	v_add_u32_e32 v218, 0x7800, v216
	v_add_u32_e32 v213, 0xb400, v224
	v_add_u32_e32 v219, 0xb400, v225
	v_and_b32_e32 v222, 31, v220
	v_lshrrev_b32_e32 v223, 5, v220
	v_bfe_u32 v224, v220, 1, 3
	v_xor_b32_e32 v223, v223, v224
	v_lshlrev_b32_e32 v223, 4, v223
	v_lshrrev_b32_e32 v224, 1, v221
	v_and_b32_e32 v225, 1, v221
	v_lshl_add_u32 v224, v224, 6, v222
	v_lshl_add_u32 v225, v225, 6, v222
	v_lshl_or_b32 v202, v224, 7, v223
	v_lshl_or_b32 v206, v225, 7, v223
	v_xor_b32_e32 v203, 32, v202
	v_xor_b32_e32 v207, 32, v206
	v_xor_b32_e32 v204, 64, v202
	v_xor_b32_e32 v208, 64, v206
	v_xor_b32_e32 v205, 96, v202
	v_xor_b32_e32 v209, 96, v206
	s_lshl_b32 s13, s13, 12
	s_sub_u32 s10, s4, 0x80
	s_subb_u32 s11, s5, 0
	s_add_u32 s8, s2, 0x1ff80
	s_addc_u32 s9, s3, 0
	s_sub_u32 s6, s2, 0x80
	s_subb_u32 s7, s3, 0
	s_mov_b32 s12, 0
	v_mov_b32_e32 v112, 0
	v_mov_b32_e32 v113, 0
	v_mov_b32_e32 v114, 0
	v_mov_b32_e32 v115, 0
	v_mov_b32_e32 v116, 0
	v_mov_b32_e32 v117, 0
	v_mov_b32_e32 v118, 0
	v_mov_b32_e32 v119, 0
	v_mov_b32_e32 v120, 0
	v_mov_b32_e32 v121, 0
	v_mov_b32_e32 v122, 0
	v_mov_b32_e32 v123, 0
	v_mov_b32_e32 v124, 0
	v_mov_b32_e32 v125, 0
	v_mov_b32_e32 v126, 0
	v_mov_b32_e32 v127, 0
	v_mov_b32_e32 v48, 0
	v_mov_b32_e32 v49, 0
	v_mov_b32_e32 v50, 0
	v_mov_b32_e32 v51, 0
	v_mov_b32_e32 v52, 0
	v_mov_b32_e32 v53, 0
	v_mov_b32_e32 v54, 0
	v_mov_b32_e32 v55, 0
	v_mov_b32_e32 v56, 0
	v_mov_b32_e32 v57, 0
	v_mov_b32_e32 v58, 0
	v_mov_b32_e32 v59, 0
	v_mov_b32_e32 v60, 0
	v_mov_b32_e32 v61, 0
	v_mov_b32_e32 v62, 0
	v_mov_b32_e32 v63, 0
	v_mov_b32_e32 v96, 0
	v_mov_b32_e32 v97, 0
	v_mov_b32_e32 v98, 0
	v_mov_b32_e32 v99, 0
	v_mov_b32_e32 v100, 0
	v_mov_b32_e32 v101, 0
	v_mov_b32_e32 v102, 0
	v_mov_b32_e32 v103, 0
	v_mov_b32_e32 v104, 0
	v_mov_b32_e32 v105, 0
	v_mov_b32_e32 v106, 0
	v_mov_b32_e32 v107, 0
	v_mov_b32_e32 v108, 0
	v_mov_b32_e32 v109, 0
	v_mov_b32_e32 v110, 0
	v_mov_b32_e32 v111, 0
	v_mov_b32_e32 v32, 0
	v_mov_b32_e32 v33, 0
	v_mov_b32_e32 v34, 0
	v_mov_b32_e32 v35, 0
	v_mov_b32_e32 v36, 0
	v_mov_b32_e32 v37, 0
	v_mov_b32_e32 v38, 0
	v_mov_b32_e32 v39, 0
	v_mov_b32_e32 v40, 0
	v_mov_b32_e32 v41, 0
	v_mov_b32_e32 v42, 0
	v_mov_b32_e32 v43, 0
	v_mov_b32_e32 v44, 0
	v_mov_b32_e32 v45, 0
	v_mov_b32_e32 v46, 0
	v_mov_b32_e32 v47, 0
	v_mov_b32_e32 v80, 0
	v_mov_b32_e32 v81, 0
	v_mov_b32_e32 v82, 0
	v_mov_b32_e32 v83, 0
	v_mov_b32_e32 v84, 0
	v_mov_b32_e32 v85, 0
	v_mov_b32_e32 v86, 0
	v_mov_b32_e32 v87, 0
	v_mov_b32_e32 v88, 0
	v_mov_b32_e32 v89, 0
	v_mov_b32_e32 v90, 0
	v_mov_b32_e32 v91, 0
	v_mov_b32_e32 v92, 0
	v_mov_b32_e32 v93, 0
	v_mov_b32_e32 v94, 0
	v_mov_b32_e32 v95, 0
	v_mov_b32_e32 v16, 0
	v_mov_b32_e32 v17, 0
	v_mov_b32_e32 v18, 0
	v_mov_b32_e32 v19, 0
	v_mov_b32_e32 v20, 0
	v_mov_b32_e32 v21, 0
	v_mov_b32_e32 v22, 0
	v_mov_b32_e32 v23, 0
	v_mov_b32_e32 v24, 0
	v_mov_b32_e32 v25, 0
	v_mov_b32_e32 v26, 0
	v_mov_b32_e32 v27, 0
	v_mov_b32_e32 v28, 0
	v_mov_b32_e32 v29, 0
	v_mov_b32_e32 v30, 0
	v_mov_b32_e32 v31, 0
	v_mov_b32_e32 v64, 0
	v_mov_b32_e32 v65, 0
	v_mov_b32_e32 v66, 0
	v_mov_b32_e32 v67, 0
	v_mov_b32_e32 v68, 0
	v_mov_b32_e32 v69, 0
	v_mov_b32_e32 v70, 0
	v_mov_b32_e32 v71, 0
	v_mov_b32_e32 v72, 0
	v_mov_b32_e32 v73, 0
	v_mov_b32_e32 v74, 0
	v_mov_b32_e32 v75, 0
	v_mov_b32_e32 v76, 0
	v_mov_b32_e32 v77, 0
	v_mov_b32_e32 v78, 0
	v_mov_b32_e32 v79, 0
	v_mov_b32_e32 v0, 0
	v_mov_b32_e32 v1, 0
	v_mov_b32_e32 v2, 0
	v_mov_b32_e32 v3, 0
	v_mov_b32_e32 v4, 0
	v_mov_b32_e32 v5, 0
	v_mov_b32_e32 v6, 0
	v_mov_b32_e32 v7, 0
	v_mov_b32_e32 v8, 0
	v_mov_b32_e32 v9, 0
	v_mov_b32_e32 v10, 0
	v_mov_b32_e32 v11, 0
	v_mov_b32_e32 v12, 0
	v_mov_b32_e32 v13, 0
	v_mov_b32_e32 v14, 0
	v_mov_b32_e32 v15, 0
	s_waitcnt lgkmcnt(0)
	s_barrier
	s_add_u32 s10, s10, 0x80
	s_addc_u32 s11, s11, 0
	s_add_u32 m0, s13, 0
	s_nop 0
	global_load_lds_dwordx4 v216, s[10:11]
	global_load_lds_dwordx4 v217, s[10:11] offset:1024
	global_load_lds_dwordx4 v218, s[10:11] offset:2048
	global_load_lds_dwordx4 v219, s[10:11] offset:3072
	s_add_u32 s6, s6, 0x80
	s_addc_u32 s7, s7, 0
	s_add_u32 m0, s13, 32768
	s_nop 0
	global_load_lds_dwordx4 v210, s[6:7]
	global_load_lds_dwordx4 v211, s[6:7] offset:1024
	global_load_lds_dwordx4 v212, s[6:7] offset:2048
	global_load_lds_dwordx4 v213, s[6:7] offset:3072
; #define GLOAD(dst, kt_) _Pragma("unroll") for (int i = 0; i < NCH; ++i) { dst[i] = (i < NCHW) ? ldw(i, tid >> 3, (kt_) * 64 + (tid & 7) * 8) : ldx(i - NCHW, tid >> 3, (kt_) * 64 + (tid & 7) * 8); }
; #define LSTORE(src, base) _Pragma("unroll") for (int i = 0; i < NCH; ++i) { const int c = tid + 256 * i; *(u32x4*)((base) + (c >> 3) * 144 + (c & 7) * 16) = src[i]; }
; template <int WGN, int INS, int IMS, bool DB, class LdW, class LdX>
; DI void gemm_core(f32x16 (&acc)[INS][IMS], const int KT, LdW ldw, LdX ldx, char* lds, const int tid) {
;     ...
;   if (DB) {
;     u32x4 preA[NCH], preB[NCH];
;     GLOAD(preA, 0)
;     GLOAD(preB, 1)
;     __syncthreads();
;     LSTORE(preA, lds)
;     __syncthreads();
;     for (int kt = 0; kt < KT; kt += 2) {
;       if (kt + 2 < KT) { GLOAD(preA, kt + 2) }
;       COMPUTE_PIPE(lds)
;       LSTORE(preB, lds + BUFB)
;       __syncthreads();
;       if (kt + 3 < KT) { GLOAD(preB, kt + 3) }
;       COMPUTE_PIPE(lds + BUFB)
;       if (kt + 2 < KT) { LSTORE(preA, lds) }
;       __syncthreads();
;     }
.Lga_loop:
	s_waitcnt vmcnt(0)
	s_barrier
	ds_read_b128 v[160:163], v206 offset:0
	ds_read_b128 v[236:239], v206 offset:4096
	ds_read_b128 v[128:131], v202 offset:32768
	ds_read_b128 v[144:147], v202 offset:36864
	ds_read_b128 v[164:167], v207 offset:0
	ds_read_b128 v[240:243], v207 offset:4096
	ds_read_b128 v[132:135], v203 offset:32768
	ds_read_b128 v[148:151], v203 offset:36864
	s_add_u32 s8, s8, 0x80
	s_addc_u32 s9, s9, 0
	s_add_u32 m0, s13, 49152
	s_nop 0
	global_load_lds_dwordx4 v210, s[8:9]
	global_load_lds_dwordx4 v211, s[8:9] offset:1024
	global_load_lds_dwordx4 v212, s[8:9] offset:2048
	global_load_lds_dwordx4 v213, s[8:9] offset:3072
	s_add_u32 s10, s10, 0x80
	s_addc_u32 s11, s11, 0
	s_add_u32 m0, s13, 16384
	s_nop 0
	global_load_lds_dwordx4 v216, s[10:11]
	global_load_lds_dwordx4 v217, s[10:11] offset:1024
	global_load_lds_dwordx4 v218, s[10:11] offset:2048
	global_load_lds_dwordx4 v219, s[10:11] offset:3072
	s_waitcnt lgkmcnt(4)
	v_mfma_f32_32x32x16_bf16 v[112:127], v[128:131], v[160:163], v[112:127]
	v_mfma_f32_32x32x16_bf16 v[48:63], v[128:131], v[236:239], v[48:63]
	ds_read_b128 v[168:171], v208 offset:0
	ds_read_b128 v[244:247], v208 offset:4096
	ds_read_b128 v[136:139], v204 offset:32768
	ds_read_b128 v[152:155], v204 offset:36864
	v_mfma_f32_32x32x16_bf16 v[96:111], v[144:147], v[160:163], v[96:111]
	v_mfma_f32_32x32x16_bf16 v[32:47], v[144:147], v[236:239], v[32:47]
	s_waitcnt lgkmcnt(4)
	v_mfma_f32_32x32x16_bf16 v[112:127], v[132:135], v[164:167], v[112:127]
	v_mfma_f32_32x32x16_bf16 v[48:63], v[132:135], v[240:243], v[48:63]
	ds_read_b128 v[172:175], v209 offset:0
	ds_read_b128 v[248:251], v209 offset:4096
	ds_read_b128 v[140:143], v205 offset:32768
	ds_read_b128 v[156:159], v205 offset:36864
	v_mfma_f32_32x32x16_bf16 v[96:111], v[148:151], v[164:167], v[96:111]
	v_mfma_f32_32x32x16_bf16 v[32:47], v[148:151], v[240:243], v[32:47]
	s_waitcnt lgkmcnt(4)
	v_mfma_f32_32x32x16_bf16 v[112:127], v[136:139], v[168:171], v[112:127]
	v_mfma_f32_32x32x16_bf16 v[48:63], v[136:139], v[244:247], v[48:63]
	v_mfma_f32_32x32x16_bf16 v[96:111], v[152:155], v[168:171], v[96:111]
	v_mfma_f32_32x32x16_bf16 v[32:47], v[152:155], v[244:247], v[32:47]
	s_waitcnt lgkmcnt(0)
	v_mfma_f32_32x32x16_bf16 v[112:127], v[140:143], v[172:175], v[112:127]
	v_mfma_f32_32x32x16_bf16 v[48:63], v[140:143], v[248:251], v[48:63]
	v_mfma_f32_32x32x16_bf16 v[96:111], v[156:159], v[172:175], v[96:111]
	v_mfma_f32_32x32x16_bf16 v[32:47], v[156:159], v[248:251], v[32:47]
	s_waitcnt vmcnt(4)
	s_barrier
	ds_read_b128 v[128:131], v202 offset:49152
	ds_read_b128 v[144:147], v202 offset:53248
	ds_read_b128 v[132:135], v203 offset:49152
	ds_read_b128 v[148:151], v203 offset:53248
	ds_read_b128 v[136:139], v204 offset:49152
	ds_read_b128 v[152:155], v204 offset:53248
	ds_read_b128 v[140:143], v205 offset:49152
	ds_read_b128 v[156:159], v205 offset:53248
	s_add_u32 s6, s6, 0x80
	s_addc_u32 s7, s7, 0
	s_add_u32 m0, s13, 32768
	s_nop 0
	global_load_lds_dwordx4 v210, s[6:7]
	global_load_lds_dwordx4 v211, s[6:7] offset:1024
	global_load_lds_dwordx4 v212, s[6:7] offset:2048
	global_load_lds_dwordx4 v213, s[6:7] offset:3072
	s_waitcnt lgkmcnt(6)
	v_mfma_f32_32x32x16_bf16 v[80:95], v[128:131], v[160:163], v[80:95]
	v_mfma_f32_32x32x16_bf16 v[16:31], v[128:131], v[236:239], v[16:31]
	v_mfma_f32_32x32x16_bf16 v[64:79], v[144:147], v[160:163], v[64:79]
	v_mfma_f32_32x32x16_bf16 v[0:15], v[144:147], v[236:239], v[0:15]
	s_waitcnt lgkmcnt(4)
	v_mfma_f32_32x32x16_bf16 v[80:95], v[132:135], v[164:167], v[80:95]
	v_mfma_f32_32x32x16_bf16 v[16:31], v[132:135], v[240:243], v[16:31]
	v_mfma_f32_32x32x16_bf16 v[64:79], v[148:151], v[164:167], v[64:79]
	v_mfma_f32_32x32x16_bf16 v[0:15], v[148:151], v[240:243], v[0:15]
	s_waitcnt lgkmcnt(2)
	v_mfma_f32_32x32x16_bf16 v[80:95], v[136:139], v[168:171], v[80:95]
	v_mfma_f32_32x32x16_bf16 v[16:31], v[136:139], v[244:247], v[16:31]
	v_mfma_f32_32x32x16_bf16 v[64:79], v[152:155], v[168:171], v[64:79]
	v_mfma_f32_32x32x16_bf16 v[0:15], v[152:155], v[244:247], v[0:15]
	s_waitcnt lgkmcnt(0)
	v_mfma_f32_32x32x16_bf16 v[80:95], v[140:143], v[172:175], v[80:95]
	v_mfma_f32_32x32x16_bf16 v[16:31], v[140:143], v[248:251], v[16:31]
	v_mfma_f32_32x32x16_bf16 v[64:79], v[156:159], v[172:175], v[64:79]
	v_mfma_f32_32x32x16_bf16 v[0:15], v[156:159], v[248:251], v[0:15]
	s_waitcnt vmcnt(0)
	s_barrier
	ds_read_b128 v[160:163], v206 offset:16384
	ds_read_b128 v[236:239], v206 offset:20480
	ds_read_b128 v[128:131], v202 offset:32768
	ds_read_b128 v[144:147], v202 offset:36864
	ds_read_b128 v[164:167], v207 offset:16384
	ds_read_b128 v[240:243], v207 offset:20480
	ds_read_b128 v[132:135], v203 offset:32768
	ds_read_b128 v[148:151], v203 offset:36864
	s_add_u32 s8, s8, 0x80
	s_addc_u32 s9, s9, 0
	s_add_u32 m0, s13, 49152
	s_nop 0
	global_load_lds_dwordx4 v210, s[8:9]
	global_load_lds_dwordx4 v211, s[8:9] offset:1024
	global_load_lds_dwordx4 v212, s[8:9] offset:2048
	global_load_lds_dwordx4 v213, s[8:9] offset:3072
	s_cmp_eq_u32 s12, 7
	s_cbranch_scc1 .Lga_skipx
	s_add_u32 s10, s10, 0x80
	s_addc_u32 s11, s11, 0
	s_add_u32 m0, s13, 0
	s_nop 0
	global_load_lds_dwordx4 v216, s[10:11]
	global_load_lds_dwordx4 v217, s[10:11] offset:1024
	global_load_lds_dwordx4 v218, s[10:11] offset:2048
	global_load_lds_dwordx4 v219, s[10:11] offset:3072
; #define GLOAD(dst, kt_) _Pragma("unroll") for (int i = 0; i < NCH; ++i) { dst[i] = (i < NCHW) ? ldw(i, tid >> 3, (kt_) * 64 + (tid & 7) * 8) : ldx(i - NCHW, tid >> 3, (kt_) * 64 + (tid & 7) * 8); }
; #define LSTORE(src, base) _Pragma("unroll") for (int i = 0; i < NCH; ++i) { const int c = tid + 256 * i; *(u32x4*)((base) + (c >> 3) * 144 + (c & 7) * 16) = src[i]; }
; template <int WGN, int INS, int IMS, bool DB, class LdW, class LdX>
; DI void gemm_core(f32x16 (&acc)[INS][IMS], const int KT, LdW ldw, LdX ldx, char* lds, const int tid) {
;     ...
;   if (DB) {
;     u32x4 preA[NCH], preB[NCH];
;     GLOAD(preA, 0)
;     GLOAD(preB, 1)
;     __syncthreads();
;     LSTORE(preA, lds)
;     __syncthreads();
;     for (int kt = 0; kt < KT; kt += 2) {
;       if (kt + 2 < KT) { GLOAD(preA, kt + 2) }
;       COMPUTE_PIPE(lds)
;       LSTORE(preB, lds + BUFB)
;       __syncthreads();
;       if (kt + 3 < KT) { GLOAD(preB, kt + 3) }
;       COMPUTE_PIPE(lds + BUFB)
;       if (kt + 2 < KT) { LSTORE(preA, lds) }
;       __syncthreads();
;     }
; template <int NTW>
; DI void inproj_tile(const Params& p, int l, int mt, int ntile, char* lds) {
;     ...
;   for (int im = 0; im < 2; ++im) {
;     const int tl = wm * 64 + im * 32 + l31;
;     const float r = rn[(size_t)mt * 128 + tl];
.Lga_skipx:
	s_waitcnt lgkmcnt(4)
	v_mfma_f32_32x32x16_bf16 v[112:127], v[128:131], v[160:163], v[112:127]
	v_mfma_f32_32x32x16_bf16 v[48:63], v[128:131], v[236:239], v[48:63]
	ds_read_b128 v[168:171], v208 offset:16384
	ds_read_b128 v[244:247], v208 offset:20480
	ds_read_b128 v[136:139], v204 offset:32768
	ds_read_b128 v[152:155], v204 offset:36864
	v_mfma_f32_32x32x16_bf16 v[96:111], v[144:147], v[160:163], v[96:111]
	v_mfma_f32_32x32x16_bf16 v[32:47], v[144:147], v[236:239], v[32:47]
	s_waitcnt lgkmcnt(4)
	v_mfma_f32_32x32x16_bf16 v[112:127], v[132:135], v[164:167], v[112:127]
	v_mfma_f32_32x32x16_bf16 v[48:63], v[132:135], v[240:243], v[48:63]
	ds_read_b128 v[172:175], v209 offset:16384
	ds_read_b128 v[248:251], v209 offset:20480
	ds_read_b128 v[140:143], v205 offset:32768
	ds_read_b128 v[156:159], v205 offset:36864
	v_mfma_f32_32x32x16_bf16 v[96:111], v[148:151], v[164:167], v[96:111]
	v_mfma_f32_32x32x16_bf16 v[32:47], v[148:151], v[240:243], v[32:47]
	s_waitcnt lgkmcnt(4)
	v_mfma_f32_32x32x16_bf16 v[112:127], v[136:139], v[168:171], v[112:127]
	v_mfma_f32_32x32x16_bf16 v[48:63], v[136:139], v[244:247], v[48:63]
	v_mfma_f32_32x32x16_bf16 v[96:111], v[152:155], v[168:171], v[96:111]
	v_mfma_f32_32x32x16_bf16 v[32:47], v[152:155], v[244:247], v[32:47]
	s_waitcnt lgkmcnt(0)
	v_mfma_f32_32x32x16_bf16 v[112:127], v[140:143], v[172:175], v[112:127]
	v_mfma_f32_32x32x16_bf16 v[48:63], v[140:143], v[248:251], v[48:63]
	v_mfma_f32_32x32x16_bf16 v[96:111], v[156:159], v[172:175], v[96:111]
	v_mfma_f32_32x32x16_bf16 v[32:47], v[156:159], v[248:251], v[32:47]
	s_cmp_eq_u32 s12, 7
	s_cbranch_scc1 .Lga_lastp1
	s_waitcnt vmcnt(4)
	s_barrier
	ds_read_b128 v[128:131], v202 offset:49152
	ds_read_b128 v[144:147], v202 offset:53248
	ds_read_b128 v[132:135], v203 offset:49152
	ds_read_b128 v[148:151], v203 offset:53248
	ds_read_b128 v[136:139], v204 offset:49152
	ds_read_b128 v[152:155], v204 offset:53248
	ds_read_b128 v[140:143], v205 offset:49152
	ds_read_b128 v[156:159], v205 offset:53248
	s_add_u32 s6, s6, 0x80
	s_addc_u32 s7, s7, 0
	s_add_u32 m0, s13, 32768
	s_nop 0
	global_load_lds_dwordx4 v210, s[6:7]
	global_load_lds_dwordx4 v211, s[6:7] offset:1024
	global_load_lds_dwordx4 v212, s[6:7] offset:2048
	global_load_lds_dwordx4 v213, s[6:7] offset:3072
	s_branch .Lga_p1c
.Lga_lastp1:
	s_waitcnt vmcnt(0)
	s_barrier
	ds_read_b128 v[128:131], v202 offset:49152
	ds_read_b128 v[144:147], v202 offset:53248
	ds_read_b128 v[132:135], v203 offset:49152
	ds_read_b128 v[148:151], v203 offset:53248
	ds_read_b128 v[136:139], v204 offset:49152
	ds_read_b128 v[152:155], v204 offset:53248
	ds_read_b128 v[140:143], v205 offset:49152
	ds_read_b128 v[156:159], v205 offset:53248
.Lga_p1c:
	s_waitcnt lgkmcnt(6)
	v_mfma_f32_32x32x16_bf16 v[80:95], v[128:131], v[160:163], v[80:95]
	v_mfma_f32_32x32x16_bf16 v[16:31], v[128:131], v[236:239], v[16:31]
	v_mfma_f32_32x32x16_bf16 v[64:79], v[144:147], v[160:163], v[64:79]
	v_mfma_f32_32x32x16_bf16 v[0:15], v[144:147], v[236:239], v[0:15]
	s_waitcnt lgkmcnt(4)
	v_mfma_f32_32x32x16_bf16 v[80:95], v[132:135], v[164:167], v[80:95]
	v_mfma_f32_32x32x16_bf16 v[16:31], v[132:135], v[240:243], v[16:31]
	v_mfma_f32_32x32x16_bf16 v[64:79], v[148:151], v[164:167], v[64:79]
	v_mfma_f32_32x32x16_bf16 v[0:15], v[148:151], v[240:243], v[0:15]
	s_waitcnt lgkmcnt(2)
	v_mfma_f32_32x32x16_bf16 v[80:95], v[136:139], v[168:171], v[80:95]
	v_mfma_f32_32x32x16_bf16 v[16:31], v[136:139], v[244:247], v[16:31]
	v_mfma_f32_32x32x16_bf16 v[64:79], v[152:155], v[168:171], v[64:79]
	v_mfma_f32_32x32x16_bf16 v[0:15], v[152:155], v[244:247], v[0:15]
	s_waitcnt lgkmcnt(0)
	v_mfma_f32_32x32x16_bf16 v[80:95], v[140:143], v[172:175], v[80:95]
	v_mfma_f32_32x32x16_bf16 v[16:31], v[140:143], v[248:251], v[16:31]
	v_mfma_f32_32x32x16_bf16 v[64:79], v[156:159], v[172:175], v[64:79]
	v_mfma_f32_32x32x16_bf16 v[0:15], v[156:159], v[248:251], v[0:15]
	s_add_i32 s12, s12, 1
	s_cmp_lg_u32 s12, 8
	s_cbranch_scc1 .Lga_loop
	s_nop 15
	s_barrier
	s_add_u32 s2, s27, 0x4a40000
	s_addc_u32 s3, s28, 0
	s_lshl_b64 s[0:1], s[0:1], 1
	s_add_u32 s0, s27, s0
	s_addc_u32 s1, s28, s1
	s_add_u32 s0, s0, 0x4a50000
	s_addc_u32 s1, s1, 0
	v_and_b32_e32 v128, 0x7fffff80, v181
	v_and_or_b32 v129, v185, 4, v128
	v_or_b32_e32 v128, s80, v183
	v_lshlrev_b32_e32 v132, 2, v128
	v_mov_b32_e32 v128, v252
	s_waitcnt vmcnt(0)
; template <int NTW>
; DI void inproj_tile(const Params& p, int l, int mt, int ntile, char* lds) {
;     ...
;   __syncthreads();
; #pragma unroll
;   for (int im = 0; im < 2; ++im) {
;     const int tl = wm * 64 + im * 32 + l31;
;     const float r = rn[(size_t)mt * 128 + tl];
; #pragma unroll
;     for (int in = 0; in < NTW; ++in)
; #pragma unroll
;       for (int g = 0; g < 4; ++g) {
;         const int n = wn * 32 * NTW + in * 32 + 8 * g + 4 * hi;
;         u32x2 o; o[0] = pk2(acc[in][im][4 * g] * r, acc[in][im][4 * g + 1] * r); o[1] = pk2(acc[in][im][4 * g + 2] * r, acc[in][im][4 * g + 3] * r);
;         *(u32x2*)(lds + tl * RS + n * 2) = o;
;       }
;   }
	s_nop 2
	v_mul_f32_e64 v112, v112, v128
	v_mul_f32_e64 v113, v113, v128
	v_cvt_pk_bf16_f32 v130, v112, v113
	v_mul_f32_e64 v112, v114, v128
	v_mul_f32_e64 v113, v115, v128
	v_mul_f32_e64 v96, v96, v128
	v_mul_f32_e64 v97, v97, v128
	v_cvt_pk_bf16_f32 v131, v112, v113
	v_lshlrev_b32_e32 v112, 1, v129
	v_mad_u32_u24 v112, v183, s73, v112
	v_pk_mul_f32 v[98:99], v[98:99], v[128:129] op_sel_hi:[1,0]
	s_nop 2
	v_pk_mul_f32 v[64:65], v[64:65], v[128:129] op_sel_hi:[1,0]
	v_pk_mul_f32 v[66:67], v[66:67], v[128:129] op_sel_hi:[1,0]
	v_cvt_pk_bf16_f32 v64, v64, v65
	v_cvt_pk_bf16_f32 v65, v66, v67
	v_pk_mul_f32 v[66:67], v[68:69], v[128:129] op_sel_hi:[1,0]
	v_pk_mul_f32 v[68:69], v[70:71], v[128:129] op_sel_hi:[1,0]
	v_cvt_pk_bf16_f32 v66, v66, v67
	v_cvt_pk_bf16_f32 v67, v68, v69
	ds_write2_b64 v112, v[64:65], v[66:67] offset0:24 offset1:26
	v_pk_mul_f32 v[64:65], v[72:73], v[128:129] op_sel_hi:[1,0]
	v_pk_mul_f32 v[66:67], v[74:75], v[128:129] op_sel_hi:[1,0]
	v_cvt_pk_bf16_f32 v64, v64, v65
	v_cvt_pk_bf16_f32 v65, v66, v67
	v_pk_mul_f32 v[66:67], v[76:77], v[128:129] op_sel_hi:[1,0]
	v_pk_mul_f32 v[68:69], v[78:79], v[128:129] op_sel_hi:[1,0]
	v_cvt_pk_bf16_f32 v66, v66, v67
	v_cvt_pk_bf16_f32 v67, v68, v69
	ds_write2_b64 v112, v[64:65], v[66:67] offset0:28 offset1:30
	v_or_b32_e32 v64, 0x80, v132
	v_mov_b32_e32 v64, v253
	v_mul_f32_e64 v114, v116, v128
	v_mul_f32_e64 v115, v117, v128
	v_mul_f32_e64 v116, v118, v128
	v_mul_f32_e64 v117, v119, v128
	v_cvt_pk_bf16_f32 v96, v96, v97
	v_cvt_pk_bf16_f32 v97, v98, v99
	v_pk_mul_f32 v[98:99], v[100:101], v[128:129] op_sel_hi:[1,0]
	v_pk_mul_f32 v[100:101], v[102:103], v[128:129] op_sel_hi:[1,0]
	v_cvt_pk_bf16_f32 v114, v114, v115
	s_nop 1
	v_mul_f32_e64 v80, v80, v128
	v_mul_f32_e64 v81, v81, v128
	v_mul_f32_e64 v82, v82, v128
	v_mul_f32_e64 v83, v83, v128
	v_cvt_pk_bf16_f32 v80, v80, v81
	v_cvt_pk_bf16_f32 v81, v82, v83
	v_pk_mul_f32 v[82:83], v[84:85], v[128:129] op_sel_hi:[1,0]
	v_pk_mul_f32 v[84:85], v[86:87], v[128:129] op_sel_hi:[1,0]
	v_cvt_pk_bf16_f32 v115, v116, v117
	v_cvt_pk_bf16_f32 v98, v98, v99
	v_cvt_pk_bf16_f32 v99, v100, v101
	v_cvt_pk_bf16_f32 v82, v82, v83
	v_cvt_pk_bf16_f32 v83, v84, v85
	ds_write2_b64 v112, v[130:131], v[114:115] offset1:2
	v_pk_mul_f32 v[114:115], v[120:121], v[128:129] op_sel_hi:[1,0]
	v_pk_mul_f32 v[116:117], v[122:123], v[128:129] op_sel_hi:[1,0]
	ds_write2_b64 v112, v[96:97], v[98:99] offset0:8 offset1:10
	v_pk_mul_f32 v[96:97], v[104:105], v[128:129] op_sel_hi:[1,0]
	v_pk_mul_f32 v[98:99], v[106:107], v[128:129] op_sel_hi:[1,0]
	ds_write2_b64 v112, v[80:81], v[82:83] offset0:16 offset1:18
	v_pk_mul_f32 v[80:81], v[88:89], v[128:129] op_sel_hi:[1,0]
	v_pk_mul_f32 v[82:83], v[90:91], v[128:129] op_sel_hi:[1,0]
	v_cvt_pk_bf16_f32 v114, v114, v115
	v_cvt_pk_bf16_f32 v115, v116, v117
	v_pk_mul_f32 v[116:117], v[124:125], v[128:129] op_sel_hi:[1,0]
	v_pk_mul_f32 v[118:119], v[126:127], v[128:129] op_sel_hi:[1,0]
	v_cvt_pk_bf16_f32 v96, v96, v97
	v_cvt_pk_bf16_f32 v97, v98, v99
	v_pk_mul_f32 v[98:99], v[108:109], v[128:129] op_sel_hi:[1,0]
	v_pk_mul_f32 v[100:101], v[110:111], v[128:129] op_sel_hi:[1,0]
	v_cvt_pk_bf16_f32 v80, v80, v81
	v_cvt_pk_bf16_f32 v81, v82, v83
	v_pk_mul_f32 v[82:83], v[92:93], v[128:129] op_sel_hi:[1,0]
	v_pk_mul_f32 v[84:85], v[94:95], v[128:129] op_sel_hi:[1,0]
	v_cvt_pk_bf16_f32 v116, v116, v117
	v_cvt_pk_bf16_f32 v117, v118, v119
	v_cvt_pk_bf16_f32 v98, v98, v99
	v_cvt_pk_bf16_f32 v99, v100, v101
	v_cvt_pk_bf16_f32 v82, v82, v83
	v_cvt_pk_bf16_f32 v83, v84, v85
	s_mov_b32 s2, 0
	ds_write2_b64 v112, v[114:115], v[116:117] offset0:4 offset1:6
	ds_write2_b64 v112, v[96:97], v[98:99] offset0:12 offset1:14
	ds_write2_b64 v112, v[80:81], v[82:83] offset0:20 offset1:22
	s_waitcnt vmcnt(0)
; template <int NTW>
; DI void inproj_tile(const Params& p, int l, int mt, int ntile, char* lds) {
;     ...
;   for (int im = 0; im < 2; ++im) {
;     const int tl = wm * 64 + im * 32 + l31;
;     const float r = rn[(size_t)mt * 128 + tl];
; #pragma unroll
;     for (int in = 0; in < NTW; ++in)
; #pragma unroll
;       for (int g = 0; g < 4; ++g) {
;         const int n = wn * 32 * NTW + in * 32 + 8 * g + 4 * hi;
;         u32x2 o; o[0] = pk2(acc[in][im][4 * g] * r, acc[in][im][4 * g + 1] * r); o[1] = pk2(acc[in][im][4 * g + 2] * r, acc[in][im][4 * g + 3] * r);
;         *(u32x2*)(lds + tl * RS + n * 2) = o;
;       }
;   }
;   __syncthreads();
	v_pk_mul_f32 v[48:49], v[48:49], v[64:65] op_sel_hi:[1,0]
	v_pk_mul_f32 v[50:51], v[50:51], v[64:65] op_sel_hi:[1,0]
	v_pk_mul_f32 v[32:33], v[32:33], v[64:65] op_sel_hi:[1,0]
	v_pk_mul_f32 v[34:35], v[34:35], v[64:65] op_sel_hi:[1,0]
	v_pk_mul_f32 v[16:17], v[16:17], v[64:65] op_sel_hi:[1,0]
	v_pk_mul_f32 v[18:19], v[18:19], v[64:65] op_sel_hi:[1,0]
	v_pk_mul_f32 v[0:1], v[0:1], v[64:65] op_sel_hi:[1,0]
	v_pk_mul_f32 v[2:3], v[2:3], v[64:65] op_sel_hi:[1,0]
	v_cvt_pk_bf16_f32 v48, v48, v49
	v_cvt_pk_bf16_f32 v49, v50, v51
	v_pk_mul_f32 v[50:51], v[52:53], v[64:65] op_sel_hi:[1,0]
	v_pk_mul_f32 v[52:53], v[54:55], v[64:65] op_sel_hi:[1,0]
	v_cvt_pk_bf16_f32 v32, v32, v33
	v_cvt_pk_bf16_f32 v33, v34, v35
	v_pk_mul_f32 v[34:35], v[36:37], v[64:65] op_sel_hi:[1,0]
	v_pk_mul_f32 v[36:37], v[38:39], v[64:65] op_sel_hi:[1,0]
	v_cvt_pk_bf16_f32 v16, v16, v17
	v_cvt_pk_bf16_f32 v17, v18, v19
	v_pk_mul_f32 v[18:19], v[20:21], v[64:65] op_sel_hi:[1,0]
	v_pk_mul_f32 v[20:21], v[22:23], v[64:65] op_sel_hi:[1,0]
	v_cvt_pk_bf16_f32 v0, v0, v1
	v_cvt_pk_bf16_f32 v1, v2, v3
	v_pk_mul_f32 v[2:3], v[4:5], v[64:65] op_sel_hi:[1,0]
	v_pk_mul_f32 v[4:5], v[6:7], v[64:65] op_sel_hi:[1,0]
	v_cvt_pk_bf16_f32 v50, v50, v51
	v_cvt_pk_bf16_f32 v51, v52, v53
	v_add_u32_e32 v54, 0x4000, v112
	v_cvt_pk_bf16_f32 v34, v34, v35
	v_cvt_pk_bf16_f32 v35, v36, v37
	v_cvt_pk_bf16_f32 v18, v18, v19
	v_cvt_pk_bf16_f32 v19, v20, v21
	v_cvt_pk_bf16_f32 v2, v2, v3
	v_cvt_pk_bf16_f32 v3, v4, v5
	ds_write2_b64 v54, v[48:49], v[50:51] offset0:64 offset1:66
	v_pk_mul_f32 v[48:49], v[56:57], v[64:65] op_sel_hi:[1,0]
	v_pk_mul_f32 v[50:51], v[58:59], v[64:65] op_sel_hi:[1,0]
	ds_write2_b64 v54, v[32:33], v[34:35] offset0:72 offset1:74
	v_pk_mul_f32 v[32:33], v[40:41], v[64:65] op_sel_hi:[1,0]
	v_pk_mul_f32 v[34:35], v[42:43], v[64:65] op_sel_hi:[1,0]
	ds_write2_b64 v54, v[16:17], v[18:19] offset0:80 offset1:82
	v_pk_mul_f32 v[16:17], v[24:25], v[64:65] op_sel_hi:[1,0]
	v_pk_mul_f32 v[18:19], v[26:27], v[64:65] op_sel_hi:[1,0]
	ds_write2_b64 v54, v[0:1], v[2:3] offset0:88 offset1:90
	v_pk_mul_f32 v[0:1], v[8:9], v[64:65] op_sel_hi:[1,0]
	v_pk_mul_f32 v[2:3], v[10:11], v[64:65] op_sel_hi:[1,0]
	v_cvt_pk_bf16_f32 v48, v48, v49
	v_cvt_pk_bf16_f32 v49, v50, v51
	v_pk_mul_f32 v[50:51], v[60:61], v[64:65] op_sel_hi:[1,0]
	v_pk_mul_f32 v[52:53], v[62:63], v[64:65] op_sel_hi:[1,0]
	v_cvt_pk_bf16_f32 v32, v32, v33
	v_cvt_pk_bf16_f32 v33, v34, v35
	v_pk_mul_f32 v[34:35], v[44:45], v[64:65] op_sel_hi:[1,0]
	v_pk_mul_f32 v[36:37], v[46:47], v[64:65] op_sel_hi:[1,0]
	v_cvt_pk_bf16_f32 v16, v16, v17
	v_cvt_pk_bf16_f32 v17, v18, v19
	v_pk_mul_f32 v[18:19], v[28:29], v[64:65] op_sel_hi:[1,0]
	v_pk_mul_f32 v[20:21], v[30:31], v[64:65] op_sel_hi:[1,0]
	v_cvt_pk_bf16_f32 v0, v0, v1
	v_cvt_pk_bf16_f32 v1, v2, v3
	v_pk_mul_f32 v[2:3], v[12:13], v[64:65] op_sel_hi:[1,0]
	v_pk_mul_f32 v[4:5], v[14:15], v[64:65] op_sel_hi:[1,0]
	v_cvt_pk_bf16_f32 v50, v50, v51
	v_cvt_pk_bf16_f32 v51, v52, v53
	v_cvt_pk_bf16_f32 v34, v34, v35
	v_cvt_pk_bf16_f32 v35, v36, v37
	v_cvt_pk_bf16_f32 v18, v18, v19
	v_cvt_pk_bf16_f32 v19, v20, v21
	v_cvt_pk_bf16_f32 v2, v2, v3
	v_cvt_pk_bf16_f32 v3, v4, v5
	ds_write2_b64 v54, v[48:49], v[50:51] offset0:68 offset1:70
	ds_write2_b64 v54, v[32:33], v[34:35] offset0:76 offset1:78
	ds_write2_b64 v54, v[16:17], v[18:19] offset0:84 offset1:86
	ds_write2_b64 v54, v[0:1], v[2:3] offset0:92 offset1:94
	s_waitcnt lgkmcnt(0)
	s_barrier

; __global__ void __launch_bounds__(256, 2) hybrid_megakernel(Params p) {
;   __shared__ __attribute__((aligned(16))) char lds[73728];
	.amdhsa_kernel _Z17hybrid_megakernel6Params
		.amdhsa_group_segment_fixed_size 73760
		.amdhsa_private_segment_fixed_size 0
		.amdhsa_kernarg_size 384
		.amdhsa_user_sgpr_count 2
		.amdhsa_user_sgpr_dispatch_ptr 0
		.amdhsa_user_sgpr_queue_ptr 0
		.amdhsa_user_sgpr_kernarg_segment_ptr 1
		.amdhsa_user_sgpr_dispatch_id 0
		.amdhsa_user_sgpr_kernarg_preload_length 0
		.amdhsa_user_sgpr_kernarg_preload_offset 0
		.amdhsa_user_sgpr_private_segment_size 0
		.amdhsa_uses_dynamic_stack 0
		.amdhsa_enable_private_segment 0
		.amdhsa_system_sgpr_workgroup_id_x 1
		.amdhsa_system_sgpr_workgroup_id_y 0
		.amdhsa_system_sgpr_workgroup_id_z 0
		.amdhsa_system_sgpr_workgroup_info 0
		.amdhsa_system_vgpr_workitem_id 2
		.amdhsa_next_free_vgpr 256
		.amdhsa_next_free_sgpr 98
		.amdhsa_accum_offset 256
		.amdhsa_reserve_vcc 1
		.amdhsa_float_round_mode_32 0
		.amdhsa_float_round_mode_16_64 0
		.amdhsa_float_denorm_mode_32 3
		.amdhsa_float_denorm_mode_16_64 3
		.amdhsa_dx10_clamp 1
		.amdhsa_ieee_mode 1
		.amdhsa_fp16_overflow 0
		.amdhsa_tg_split 0
		.amdhsa_exception_fp_ieee_invalid_op 0
		.amdhsa_exception_fp_denorm_src 0
		.amdhsa_exception_fp_ieee_div_zero 0
		.amdhsa_exception_fp_ieee_overflow 0
		.amdhsa_exception_fp_ieee_underflow 0
		.amdhsa_exception_fp_ieee_inexact 0
		.amdhsa_exception_int_div_zero 0
	.end_amdhsa_kernel

; __global__ void __launch_bounds__(256, 2) hybrid_megakernel(Params p) {
;   __shared__ __attribute__((aligned(16))) char lds[73728];
amdhsa.kernels:
  - .agpr_count:     0
    .args:
      - .offset:         0
        .size:           128
        .value_kind:     by_value
      - .offset:         128
        .size:           4
        .value_kind:     hidden_block_count_x
      - .offset:         132
        .size:           4
        .value_kind:     hidden_block_count_y
      - .offset:         136
        .size:           4
        .value_kind:     hidden_block_count_z
      - .offset:         140
        .size:           2
        .value_kind:     hidden_group_size_x
      - .offset:         142
        .size:           2
        .value_kind:     hidden_group_size_y
      - .offset:         144
        .size:           2
        .value_kind:     hidden_group_size_z
      - .offset:         146
        .size:           2
        .value_kind:     hidden_remainder_x
      - .offset:         148
        .size:           2
        .value_kind:     hidden_remainder_y
      - .offset:         150
        .size:           2
        .value_kind:     hidden_remainder_z
      - .offset:         168
        .size:           8
        .value_kind:     hidden_global_offset_x
      - .offset:         176
        .size:           8
        .value_kind:     hidden_global_offset_y
      - .offset:         184
        .size:           8
        .value_kind:     hidden_global_offset_z
      - .offset:         192
        .size:           2
        .value_kind:     hidden_grid_dims
      - .offset:         216
        .size:           8
        .value_kind:     hidden_multigrid_sync_arg
    .group_segment_fixed_size: 73760
    .kernarg_segment_align: 8
    .kernarg_segment_size: 384
    .language:       OpenCL C
    .language_version:
      - 2
      - 0
    .max_flat_workgroup_size: 256
    .name:           _Z17hybrid_megakernel6Params
    .private_segment_fixed_size: 0
    .sgpr_count:     104
    .sgpr_spill_count: 167
    .symbol:         _Z17hybrid_megakernel6Params.kd
    .uniform_work_group_size: 1
    .uses_dynamic_stack: false
    .vgpr_count:     256
    .vgpr_spill_count: 0
    .wavefront_size: 64
